# SB and SWA K/V tile loaders issue all tiles' loads in one round (was 4 tiles at a time)
# speedup vs baseline: 1.0085x; 1.0026x over previous
; #define LAS __attribute__((address_space(3)))
; DI void coop_load_tiles(const bf16_t* kbase, int vdelta, int t_hi, int nt, LAS unsigned char* lds, int wid, int lane) {
; #pragma unroll 1
;     for (int s0 = 0; s0 < nt; s0 += 4) {
;         u32x4 kr[4], vr[4];
; #pragma unroll
;         for (int s = 0; s < 4; ++s) if (s0 + s < nt) { const bf16_t* src = kbase + (size_t)((t_hi - s0 - s) * 64 + lane) * PITCH + 8 * wid; kr[s] = *(const u32x4*)src; vr[s] = *(const u32x4*)(src + vdelta); }
; #pragma unroll
;         for (int s = 0; s < 4; ++s) if (s0 + s < nt) { *(LAS u32x4*)(lds + (s0 + s) * 16384 + wid * 1024 + lane * 16) = kr[s];
;             *(LAS u32x4*)(lds + (s0 + s) * 16384 + 8192 + (wid >> 2) * 4096 + lane * 64 + (wid & 3) * 16) = vr[s]; }
;     }
; }
; DI void sb_wg_unit(bf16_t* act, int b, int hh, int Qb, LAS unsigned char* lds, volatile LAS unsigned* ctl, int tid, int wid, int lane) {
;     ...
;         const int t_bot = (t_top - 7) > 0 ? (t_top - 7) : 0, nt = t_top - t_bot + 1;
;         __syncthreads();
;         if (tid == 0) ctl[7] = 0u;
;         coop_load_tiles(kgb, C_VA - C_KA, t_top, nt, lds, wid, lane);
;         __syncthreads();
; #pragma unroll 1
;         while (!done && t >= t_bot) {
;             const int kv0 = t * 64;
;             LAS const unsigned char* Ks = lds + (t_top - t) * 16384; LAS const unsigned char* Vs = Ks + 8192;
.LBB0_336:
	s_barrier
	s_and_saveexec_b64 s[10:11], s[40:41]
	v_mov_b32_e32 v34, s5
	ds_write_b32 v34, v1
	s_or_b64 exec, exec, s[10:11]
	s_max_i32 s22, s25, 6
	s_add_i32 s23, s22, -6
	s_sub_i32 s26, s25, s23
	s_cmp_lt_i32 s26, 0
	s_cbranch_scc1 .LBB0_353
	v_lshl_add_u32 v87, s25, 6, v94
	v_add_u32_e32 v136, 0xc0, v87
	v_lshl_add_u64 v[138:139], s[6:7], 0, v[146:147]
	v_mad_i64_i32 v[138:139], s[10:11], v136, s31, v[138:139]
	global_load_dwordx4 v[34:37], v[138:139], off offset:1024
	global_load_dwordx4 v[108:111], v[138:139], off offset:2048
	s_cmp_lt_i32 s26, 1
	s_cbranch_scc1 .Lsbl_ld_end
	v_add_u32_e32 v136, 0x80, v87
	v_lshl_add_u64 v[138:139], s[6:7], 0, v[146:147]
	v_mad_i64_i32 v[138:139], s[10:11], v136, s31, v[138:139]
	global_load_dwordx4 v[38:41], v[138:139], off offset:1024
	global_load_dwordx4 v[112:115], v[138:139], off offset:2048
	s_cmp_lt_i32 s26, 2
	s_cbranch_scc1 .Lsbl_ld_end
	v_add_u32_e32 v136, 64, v87
	v_lshl_add_u64 v[138:139], s[6:7], 0, v[146:147]
	v_mad_i64_i32 v[138:139], s[10:11], v136, s31, v[138:139]
	global_load_dwordx4 v[42:45], v[138:139], off offset:1024
	global_load_dwordx4 v[116:119], v[138:139], off offset:2048
	s_cmp_lt_i32 s26, 3
	s_cbranch_scc1 .Lsbl_ld_end
	v_add_u32_e32 v136, 0, v87
	v_lshl_add_u64 v[138:139], s[6:7], 0, v[146:147]
	v_mad_i64_i32 v[138:139], s[10:11], v136, s31, v[138:139]
	global_load_dwordx4 v[46:49], v[138:139], off offset:1024
	global_load_dwordx4 v[120:123], v[138:139], off offset:2048
	s_cmp_lt_i32 s26, 4
	s_cbranch_scc1 .Lsbl_ld_end
	v_add_u32_e32 v136, 0xffffffc0, v87
	v_lshl_add_u64 v[138:139], s[6:7], 0, v[146:147]
	v_mad_i64_i32 v[138:139], s[10:11], v136, s31, v[138:139]
	global_load_dwordx4 v[50:53], v[138:139], off offset:1024
	global_load_dwordx4 v[124:127], v[138:139], off offset:2048
	s_cmp_lt_i32 s26, 5
	s_cbranch_scc1 .Lsbl_ld_end
	v_add_u32_e32 v136, 0xffffff80, v87
	v_lshl_add_u64 v[138:139], s[6:7], 0, v[146:147]
	v_mad_i64_i32 v[138:139], s[10:11], v136, s31, v[138:139]
	global_load_dwordx4 v[54:57], v[138:139], off offset:1024
	global_load_dwordx4 v[128:131], v[138:139], off offset:2048
	s_cmp_lt_i32 s26, 6
	s_cbranch_scc1 .Lsbl_ld_end
	v_add_u32_e32 v136, 0xffffff40, v87
	v_lshl_add_u64 v[138:139], s[6:7], 0, v[146:147]
	v_mad_i64_i32 v[138:139], s[10:11], v136, s31, v[138:139]
	global_load_dwordx4 v[58:61], v[138:139], off offset:1024
	global_load_dwordx4 v[132:135], v[138:139], off offset:2048
.Lsbl_ld_end:
	v_add_u32_e32 v90, 0x10000, v93
	v_add_u32_e32 v97, 0x10000, v92
	s_waitcnt vmcnt(0)
	ds_write_b128 v93, v[34:37]
	ds_write_b128 v92, v[108:111]
	s_cmp_lt_i32 s26, 1
	s_cbranch_scc1 .Lsbl_wr_end
	ds_write_b128 v93, v[38:41] offset:16384
	ds_write_b128 v92, v[112:115] offset:16384
	s_cmp_lt_i32 s26, 2
	s_cbranch_scc1 .Lsbl_wr_end
	ds_write_b128 v93, v[42:45] offset:32768
	ds_write_b128 v92, v[116:119] offset:32768
	s_cmp_lt_i32 s26, 3
	s_cbranch_scc1 .Lsbl_wr_end
	ds_write_b128 v93, v[46:49] offset:49152
	ds_write_b128 v92, v[120:123] offset:49152
	s_cmp_lt_i32 s26, 4
	s_cbranch_scc1 .Lsbl_wr_end
	ds_write_b128 v90, v[50:53]
	ds_write_b128 v97, v[124:127]
	s_cmp_lt_i32 s26, 5
	s_cbranch_scc1 .Lsbl_wr_end
	ds_write_b128 v90, v[54:57] offset:16384
	ds_write_b128 v97, v[128:131] offset:16384
	s_cmp_lt_i32 s26, 6
	s_cbranch_scc1 .Lsbl_wr_end
	ds_write_b128 v90, v[58:61] offset:32768
	ds_write_b128 v97, v[132:135] offset:32768
.Lsbl_wr_end:
.LBB0_353:
	s_cmp_lt_i32 s24, s23
	s_cselect_b64 s[10:11], -1, 0
	s_or_b64 s[10:11], s[8:9], s[10:11]
	s_and_b64 vcc, exec, s[10:11]
	s_waitcnt lgkmcnt(0)
	s_barrier
	v_lshlrev_b32_e32 v142, 1, v82
	v_mov_b32_e32 v143, v1
	v_lshl_add_u64 v[142:143], v[88:89], 0, v[142:143]
	global_load_dwordx2 v[160:161], v[142:143], off offset:3072
	global_load_dwordx2 v[162:163], v[142:143], off offset:3088
	global_load_dwordx2 v[164:165], v[142:143], off offset:3104
	global_load_dwordx2 v[166:167], v[142:143], off offset:3120
	global_load_dwordx2 v[168:169], v[142:143], off offset:3136
	global_load_dwordx2 v[170:171], v[142:143], off offset:3152
	global_load_dwordx2 v[172:173], v[142:143], off offset:3168
	global_load_dwordx2 v[174:175], v[142:143], off offset:3184
	s_cbranch_vccnz .LBB0_356
	s_lshl_b32 s8, s24, 6
	s_or_b32 s12, s8, 63
	s_lshl_b32 s8, s24, 14
	s_lshl_b32 s13, s25, 14
	v_subrev_u32_e32 v87, s8, v95
	v_subrev_u32_e32 v97, s8, v96

; #define LAS __attribute__((address_space(3)))
; DI void coop_load_tiles(const bf16_t* kbase, int vdelta, int t_hi, int nt, LAS unsigned char* lds, int wid, int lane) {
; #pragma unroll 1
;     for (int s0 = 0; s0 < nt; s0 += 4) {
;         u32x4 kr[4], vr[4];
; #pragma unroll
;         for (int s = 0; s < 4; ++s) if (s0 + s < nt) { const bf16_t* src = kbase + (size_t)((t_hi - s0 - s) * 64 + lane) * PITCH + 8 * wid; kr[s] = *(const u32x4*)src; vr[s] = *(const u32x4*)(src + vdelta); }
; #pragma unroll
;         for (int s = 0; s < 4; ++s) if (s0 + s < nt) { *(LAS u32x4*)(lds + (s0 + s) * 16384 + wid * 1024 + lane * 16) = kr[s];
;             *(LAS u32x4*)(lds + (s0 + s) * 16384 + 8192 + (wid >> 2) * 4096 + lane * 64 + (wid & 3) * 16) = vr[s]; }
;     }
; }
; DI void swa_wg_unit(bf16_t* act, int b, int hk, int Qb, const float* sinks_l, LAS const float* tabS, LAS unsigned char* lds, int wid, int lane) {
;     const int r = lane & 31, h = lane >> 5;
;     const int Q = Qb * 256, q0 = Q + 32 * wid, qpos = q0 + r;
;     const size_t rowq = (size_t)b * SEQ + qpos;
;     const int t_hi = (Q >> 6) + 3, t_lo = (Q >= 128) ? ((Q - 128) >> 6) : 0;
;     __syncthreads();
;     coop_load_tiles(act + (size_t)b * SEQ * PITCH + C_KC + hk * 64, C_VC - C_KC, t_hi, t_hi - t_lo + 1, lds, wid, lane);
;     __syncthreads();
;     const int tlo = (q0 >= 127) ? ((q0 - 127) >> 6) : 0;
.LBB0_361:
	s_and_b32 s10, s22, 31
	s_lshl_b32 s26, s10, 8
	s_and_b32 s24, s20, 31
	s_ashr_i32 s8, s22, 6
	s_lshl_b32 s11, s10, 2
	s_add_i32 s12, s26, 0xffffff80
	s_lshl_b32 s23, s24, 8
	s_lshr_b32 s25, s22, 5
	s_ashr_i32 s9, s8, 31
	s_or_b32 s11, s11, 3
	s_ashr_i32 s12, s12, 6
	s_cmp_lg_u32 s10, 0
	s_cselect_b32 s10, s12, 0
	s_sub_i32 s27, s11, s10
	s_cmp_lt_i32 s27, 0
	s_waitcnt lgkmcnt(0)
	s_barrier
	s_cbranch_scc1 .LBB0_376
	s_and_b32 s10, s25, 1
	s_lshl_b32 s12, s10, 7
	s_mul_i32 s14, s8, 0x6400000
	s_mul_hi_i32 s13, s8, 0x6400000
	s_or_b32 s10, s14, s12
	s_add_u32 s10, s18, s10
	s_addc_u32 s11, s19, s13
	s_add_u32 s10, s10, 0x3402000
	s_addc_u32 s11, s11, 0
	v_add_u32_e32 v52, s23, v148
	v_mov_b32_e32 v51, 0
	v_add_u32_e32 v50, 0xc0, v52
	v_mul_u32_u24_e32 v50, 0x3200, v50
	v_lshl_add_u64 v[54:55], s[10:11], 0, v[50:51]
	v_lshl_add_u64 v[54:55], v[54:55], 0, v[146:147]
	global_load_dwordx4 v[2:5], v[54:55], off offset:1024
	global_load_dwordx4 v[26:29], v[54:55], off offset:1280
	s_cmp_lt_i32 s27, 1
	s_cbranch_scc1 .Lswl_ld_end
	v_add_u32_e32 v50, 0x80, v52
	v_mul_u32_u24_e32 v50, 0x3200, v50
	v_lshl_add_u64 v[54:55], s[10:11], 0, v[50:51]
	v_lshl_add_u64 v[54:55], v[54:55], 0, v[146:147]
	global_load_dwordx4 v[6:9], v[54:55], off offset:1024
	global_load_dwordx4 v[30:33], v[54:55], off offset:1280
	s_cmp_lt_i32 s27, 2
	s_cbranch_scc1 .Lswl_ld_end
	v_add_u32_e32 v50, 64, v52
	v_mul_u32_u24_e32 v50, 0x3200, v50
	v_lshl_add_u64 v[54:55], s[10:11], 0, v[50:51]
	v_lshl_add_u64 v[54:55], v[54:55], 0, v[146:147]
	global_load_dwordx4 v[10:13], v[54:55], off offset:1024
	global_load_dwordx4 v[34:37], v[54:55], off offset:1280
	s_cmp_lt_i32 s27, 3
	s_cbranch_scc1 .Lswl_ld_end
	v_add_u32_e32 v50, 0, v52
	v_mul_u32_u24_e32 v50, 0x3200, v50
	v_lshl_add_u64 v[54:55], s[10:11], 0, v[50:51]
	v_lshl_add_u64 v[54:55], v[54:55], 0, v[146:147]
	global_load_dwordx4 v[14:17], v[54:55], off offset:1024
	global_load_dwordx4 v[38:41], v[54:55], off offset:1280
	s_cmp_lt_i32 s27, 4
	s_cbranch_scc1 .Lswl_ld_end
	v_add_u32_e32 v50, 0xffffffc0, v52
	v_mul_u32_u24_e32 v50, 0x3200, v50
	v_lshl_add_u64 v[54:55], s[10:11], 0, v[50:51]
	v_lshl_add_u64 v[54:55], v[54:55], 0, v[146:147]
	global_load_dwordx4 v[18:21], v[54:55], off offset:1024
	global_load_dwordx4 v[42:45], v[54:55], off offset:1280
	s_cmp_lt_i32 s27, 5
	s_cbranch_scc1 .Lswl_ld_end
	v_add_u32_e32 v50, 0xffffff80, v52
	v_mul_u32_u24_e32 v50, 0x3200, v50
	v_lshl_add_u64 v[54:55], s[10:11], 0, v[50:51]
	v_lshl_add_u64 v[54:55], v[54:55], 0, v[146:147]
	global_load_dwordx4 v[22:25], v[54:55], off offset:1024
	global_load_dwordx4 v[46:49], v[54:55], off offset:1280
.Lswl_ld_end:
	v_add_u32_e32 v56, 0x10000, v110
	v_add_u32_e32 v57, 0x10000, v109
	s_waitcnt vmcnt(0)
	ds_write_b128 v110, v[2:5]
	ds_write_b128 v109, v[26:29]
	s_cmp_lt_i32 s27, 1
	s_cbranch_scc1 .Lswl_wr_end
	ds_write_b128 v110, v[6:9] offset:16384
	ds_write_b128 v109, v[30:33] offset:16384
	s_cmp_lt_i32 s27, 2
	s_cbranch_scc1 .Lswl_wr_end
	ds_write_b128 v110, v[10:13] offset:32768
	ds_write_b128 v109, v[34:37] offset:32768
	s_cmp_lt_i32 s27, 3
	s_cbranch_scc1 .Lswl_wr_end
	ds_write_b128 v110, v[14:17] offset:49152
	ds_write_b128 v109, v[38:41] offset:49152
	s_cmp_lt_i32 s27, 4
	s_cbranch_scc1 .Lswl_wr_end
	ds_write_b128 v56, v[18:21]
	ds_write_b128 v57, v[42:45]
	s_cmp_lt_i32 s27, 5
	s_cbranch_scc1 .Lswl_wr_end
	ds_write_b128 v56, v[22:25] offset:16384
	ds_write_b128 v57, v[46:49] offset:16384
.Lswl_wr_end:
.LBB0_376:
	s_add_i32 s11, s26, s21
	v_or_b32_e32 v2, s11, v107
	s_lshl_b64 s[8:9], s[8:9], 13
	v_ashrrev_i32_e32 v3, 31, v2
	v_lshl_add_u64 v[2:3], s[8:9], 0, v[2:3]
	s_add_i32 s8, s11, 0xffffff81
	s_lshl_b32 s12, s24, 16
	s_and_b32 s10, s25, 1
	s_lshr_b32 s8, s8, 6
	s_cmpk_gt_i32 s11, 0x7e
	v_mov_b64_e32 v[4:5], s[76:77]
	s_cselect_b32 s24, s8, 0
	v_mad_u64_u32 v[4:5], s[8:9], v2, s31, v[4:5]
	v_mad_i32_i24 v5, v3, s31, v5
	v_mov_b32_e32 v97, v1
	s_lshl_b32 s14, s10, 2
	s_ashr_i32 s15, s11, 6
	v_lshl_add_u64 v[2:3], v[4:5], 0, v[96:97]
	s_mov_b64 s[10:11], 0x2600
	v_mov_b32_e32 v99, v1
	s_cmp_le_i32 s24, s15
	v_lshl_add_u64 v[100:101], v[2:3], 0, s[10:11]
	v_lshl_add_u64 v[2:3], v[4:5], 0, v[98:99]
	s_mov_b64 s[10:11], 0x2000
	s_cselect_b64 s[8:9], -1, 0
	v_lshl_add_u64 v[102:103], v[2:3], 0, s[10:11]
	v_add_u32_e32 v0, s23, v114
	s_lshl_b32 s10, s24, 6
	v_subrev_u32_e32 v97, s10, v0
	s_lshl_b32 s10, s24, 14
	s_mov_b32 s13, 0
	s_add_i32 s23, s24, -1
	v_subrev_u32_e32 v99, s10, v115
	v_subrev_u32_e32 v117, s10, v116
	s_waitcnt lgkmcnt(0)
	s_barrier
	s_branch .LBB0_378
